# v074 plus unit-order computation of P1/P8/P14: generic division emulation (v_rcp_iflag, readfirstlane, fix-ups) replaced by shift and mask since the row-group size is always 8
# baseline (speedup 1.0000x reference)
;     __host__ __device__ bool next(int i, Unit& u) const {
;         const long L = (long)i * G + c; if (L >= nwg) return false;
;         int wgid = (int)L; { const int q = nwg / NXCD, r = nwg % NXCD, xcd = wgid % NXCD, off = wgid / NXCD; wgid = (xcd < r ? xcd * (q + 1) : r * (q + 1) + (xcd - r) * q) + off; }
;         const int nig = WGM * nN, gid = wgid / nig, fm = gid * WGM, gsz = (nM - fm) < WGM ? (nM - fm) : WGM;
;         u.pm = fm + ((wgid % nig) % gsz); u.pn = (wgid % nig) / gsz; return true;
.LBB0_292:
	s_add_i32 s57, s57, 1
	s_mul_i32 s2, s57, s70
	s_mul_hi_u32 s3, s57, s71
	s_add_i32 s3, s3, s2
	s_mul_i32 s2, s57, s71
	s_add_u32 s2, s2, s96
	s_addc_u32 s3, s3, s45
	v_cmp_gt_i64_e32 vcc, s[2:3], v[214:215]
	v_cmp_lt_i64_e64 s[4:5], s[2:3], v[212:213]
	s_cbranch_vccnz .LBB0_294
	s_ashr_i32 s3, s2, 31
	s_lshr_b32 s3, s3, 29
	s_add_i32 s3, s2, s3
	s_ashr_i32 s16, s3, 3
	s_and_b32 s3, s3, -8
	s_sub_i32 s2, s2, s3
	s_cmp_lt_i32 s2, 0
	s_cselect_b32 s3, s52, 0xc0
	s_mul_i32 s2, s2, s3
	s_add_i32 s2, s2, s16
	s_mul_hi_i32 s3, s2, 0x2aaaaaab
	s_lshr_b32 s16, s3, 31
	s_ashr_i32 s3, s3, 4
	s_add_i32 s3, s3, s16
	s_lshl_b32 s16, s3, 3
	s_mulk_i32 s3, 0x60
	s_sub_i32 s2, s2, s3
	s_ashr_i32 s80, s2, 3
	s_and_b32 s2, s2, 7
	s_add_i32 s16, s16, s2

;     __host__ __device__ bool next(int i, Unit& u) const {
;         const long L = (long)i * G + c; if (L >= nwg) return false;
;         int wgid = (int)L; { const int q = nwg / NXCD, r = nwg % NXCD, xcd = wgid % NXCD, off = wgid / NXCD; wgid = (xcd < r ? xcd * (q + 1) : r * (q + 1) + (xcd - r) * q) + off; }
;         const int nig = WGM * nN, gid = wgid / nig, fm = gid * WGM, gsz = (nM - fm) < WGM ? (nM - fm) : WGM;
;         u.pm = fm + ((wgid % nig) % gsz); u.pn = (wgid % nig) / gsz; return true;
.LBB0_1046:
	s_add_i32 s46, s46, 1
	s_mul_i32 s1, s46, s49
	s_mul_hi_u32 s2, s46, s50
	s_add_i32 s1, s2, s1
	s_mul_i32 s2, s46, s50
	s_add_u32 s2, s2, s96
	s_addc_u32 s3, s1, s40
	v_cmp_gt_i64_e32 vcc, s[2:3], v[142:143]
	v_cmp_lt_i64_e64 s[4:5], s[2:3], v[140:141]
	s_cbranch_vccnz .LBB0_1048
	s_ashr_i32 s1, s2, 31
	s_lshr_b32 s1, s1, 29
	s_add_i32 s1, s2, s1
	s_ashr_i32 s3, s1, 3
	s_and_b32 s1, s1, -8
	s_sub_i32 s1, s2, s1
	s_cmp_lt_i32 s1, 0
	s_cselect_b32 s2, s41, 0x160
	s_mul_i32 s1, s1, s2
	s_add_i32 s1, s1, s3
	s_mul_hi_i32 s2, s1, 0x2e8ba2e9
	s_lshr_b32 s3, s2, 31
	s_ashr_i32 s2, s2, 5
	s_add_i32 s2, s2, s3
	s_lshl_b32 s3, s2, 3
	s_mulk_i32 s2, 0xb0
	s_sub_i32 s1, s1, s2
	s_ashr_i32 s55, s1, 3
	s_and_b32 s1, s1, 7
	s_add_i32 s18, s3, s1
